# K2: DPP cross-lane reductions in top-k selection and LayerNorm (replacing ds_bpermute round trips)
# speedup vs baseline: 1.0904x; 1.0083x over previous
.LBB0_900:
	v_max_u32_e32 v54, v35, v34
	v_max3_u32 v54, v54, v37, v36
	v_max3_u32 v54, v54, v39, v38
	v_max3_u32 v54, v54, v44, v43
	v_max3_u32 v54, v54, v46, v45
	v_max3_u32 v54, v54, v48, v47
	v_max3_u32 v54, v54, v50, v49
	v_max3_u32 v54, v54, v52, v51
	s_nop 1
	v_max_u32_dpp v54, v54, v54 quad_perm:[1,0,3,2] row_mask:0xf bank_mask:0xf
	s_nop 1
	v_max_u32_dpp v54, v54, v54 quad_perm:[2,3,0,1] row_mask:0xf bank_mask:0xf
	s_nop 1
	v_max_u32_dpp v54, v54, v54 row_half_mirror row_mask:0xf bank_mask:0xf
	v_cmp_ne_u32_e32 vcc, 0, v54
	s_and_saveexec_b64 s[0:1], vcc
	s_cbranch_execz .LBB0_899
	v_cmp_eq_u32_e32 vcc, v35, v54
	s_nop 1
	v_cndmask_b32_e64 v35, v35, 0, vcc
	v_cndmask_b32_e64 v55, 0, 1, vcc
	v_cmp_eq_u32_e32 vcc, v34, v54
	s_nop 1
	v_cndmask_b32_e64 v34, v34, 0, vcc
	v_cndmask_b32_e64 v56, 0, 2, vcc
	v_cmp_eq_u32_e32 vcc, v37, v54
	s_nop 1
	v_cndmask_b32_e64 v37, v37, 0, vcc
	v_cndmask_b32_e64 v57, 0, 4, vcc
	v_cmp_eq_u32_e32 vcc, v36, v54
	v_or3_b32 v55, v56, v55, v57
	s_nop 0
	v_cndmask_b32_e64 v36, v36, 0, vcc
	v_cndmask_b32_e64 v58, 0, 8, vcc
	v_cmp_eq_u32_e32 vcc, v39, v54
	s_nop 1
	v_cndmask_b32_e64 v39, v39, 0, vcc
	v_cndmask_b32_e64 v59, 0, 16, vcc
	v_cmp_eq_u32_e32 vcc, v38, v54
	v_or3_b32 v55, v55, v58, v59
	s_nop 0
	v_cndmask_b32_e64 v38, v38, 0, vcc
	v_cndmask_b32_e64 v60, 0, 32, vcc
	v_cmp_eq_u32_e32 vcc, v44, v54
	s_nop 1
	v_cndmask_b32_e64 v44, v44, 0, vcc
	v_cndmask_b32_e64 v61, 0, 64, vcc
	v_cmp_eq_u32_e32 vcc, v43, v54
	v_or3_b32 v55, v55, v60, v61
	s_nop 0
	v_cndmask_b32_e64 v43, v43, 0, vcc
	v_cndmask_b32_e32 v62, 0, v171, vcc
	v_cmp_eq_u32_e32 vcc, v46, v54
	s_nop 1
	v_cndmask_b32_e64 v46, v46, 0, vcc
	v_cndmask_b32_e32 v63, 0, v172, vcc
	v_cmp_eq_u32_e32 vcc, v45, v54
	v_or3_b32 v55, v55, v62, v63
	s_nop 0
	v_cndmask_b32_e64 v45, v45, 0, vcc
	v_cndmask_b32_e32 v64, 0, v173, vcc
	v_cmp_eq_u32_e32 vcc, v48, v54
	s_nop 1
	v_cndmask_b32_e64 v48, v48, 0, vcc
	v_cndmask_b32_e32 v65, 0, v174, vcc
	v_cmp_eq_u32_e32 vcc, v47, v54
	v_or3_b32 v55, v55, v64, v65
	s_nop 0
	v_cndmask_b32_e64 v47, v47, 0, vcc
	v_cndmask_b32_e32 v66, 0, v175, vcc
	v_cmp_eq_u32_e32 vcc, v50, v54
	s_nop 1
	v_cndmask_b32_e64 v50, v50, 0, vcc
	v_cndmask_b32_e32 v67, 0, v176, vcc
	v_cmp_eq_u32_e32 vcc, v49, v54
	v_or3_b32 v55, v55, v66, v67
	s_nop 0
	v_cndmask_b32_e64 v49, v49, 0, vcc
	v_cndmask_b32_e32 v68, 0, v177, vcc
	v_cmp_eq_u32_e32 vcc, v52, v54
	s_nop 1
	v_cndmask_b32_e64 v52, v52, 0, vcc
	v_cndmask_b32_e32 v69, 0, v163, vcc
	v_cmp_eq_u32_e32 vcc, v51, v54
	v_or3_b32 v55, v55, v68, v69
	s_nop 0
	v_cndmask_b32_e32 v54, 0, v178, vcc
	v_cndmask_b32_e64 v51, v51, 0, vcc
	v_or3_b32 v40, v55, v54, v40
	s_branch .LBB0_899

.LBB0_1058:
	v_ashrrev_i32_e32 v7, 31, v6
	v_lshlrev_b64 v[2:3], 12, v[6:7]
	v_lshl_add_u64 v[24:25], v[14:15], 0, v[2:3]
	global_load_dwordx4 v[2:5], v[24:25], off
	global_load_dwordx4 v[26:29], v[24:25], off offset:1024
	v_lshlrev_b64 v[22:23], 10, v[6:7]
	s_mov_b32 s0, 0x800000
	v_readlane_b32 s2, v232, 16
	v_readlane_b32 s3, v232, 17
	s_waitcnt vmcnt(1)
	v_mov_b32_e32 v30, v2
	s_waitcnt vmcnt(0)
	v_mov_b32_e32 v31, v26
	v_mov_b32_e32 v32, v3
	v_mov_b32_e32 v33, v27
	v_pk_add_f32 v[30:31], v[30:31], v[32:33]
	v_mov_b32_e32 v32, v4
	v_mov_b32_e32 v33, v28
	v_pk_add_f32 v[30:31], v[32:33], v[30:31]
	v_mov_b32_e32 v32, v5
	v_mov_b32_e32 v33, v29
	v_pk_add_f32 v[30:31], v[32:33], v[30:31]
	s_nop 0
	v_add_f32_e32 v0, 0, v30
	v_add_f32_e32 v0, v0, v31
	global_load_dwordx4 v[30:33], v[24:25], off offset:2048
	global_load_dwordx4 v[46:49], v[24:25], off offset:3072
	s_waitcnt vmcnt(1)
	v_mov_b32_e32 v34, v30
	s_waitcnt vmcnt(0)
	v_mov_b32_e32 v35, v46
	v_mov_b32_e32 v36, v31
	v_mov_b32_e32 v37, v47
	v_pk_add_f32 v[34:35], v[34:35], v[36:37]
	v_mov_b32_e32 v36, v32
	v_mov_b32_e32 v37, v48
	v_pk_add_f32 v[34:35], v[36:37], v[34:35]
	v_mov_b32_e32 v36, v33
	v_mov_b32_e32 v37, v49
	v_pk_add_f32 v[34:35], v[36:37], v[34:35]
	s_nop 0
	v_add_f32_e32 v0, v0, v34
	v_add_f32_e32 v0, v0, v35
	s_nop 1
	v_add_f32_dpp v0, v0, v0 quad_perm:[1,0,3,2] row_mask:0xf bank_mask:0xf
	s_nop 1
	v_add_f32_dpp v0, v0, v0 quad_perm:[2,3,0,1] row_mask:0xf bank_mask:0xf
	s_nop 1
	v_add_f32_dpp v0, v0, v0 row_half_mirror row_mask:0xf bank_mask:0xf
	s_nop 1
	v_add_f32_dpp v0, v0, v0 row_mirror row_mask:0xf bank_mask:0xf
	s_nop 1
	v_readlane_b32 s8, v0, 0
	v_readlane_b32 s9, v0, 16
	v_readlane_b32 s10, v0, 32
	v_readlane_b32 s11, v0, 48
	s_nop 1
	v_mov_b32_e32 v0, s8
	v_add_f32_e32 v0, s9, v0
	v_add_f32_e32 v0, s10, v0
	v_add_f32_e32 v0, s11, v0
	v_mul_f32_e32 v0, 0x3a800000, v0
	v_pk_add_f32 v[34:35], v[26:27], v[0:1] op_sel_hi:[1,0] neg_lo:[0,1] neg_hi:[0,1]
	v_pk_add_f32 v[36:37], v[28:29], v[0:1] op_sel_hi:[1,0] neg_lo:[0,1] neg_hi:[0,1]
	v_pk_add_f32 v[26:27], v[46:47], v[0:1] op_sel_hi:[1,0] neg_lo:[0,1] neg_hi:[0,1]
	v_pk_add_f32 v[28:29], v[48:49], v[0:1] op_sel_hi:[1,0] neg_lo:[0,1] neg_hi:[0,1]
	global_load_dwordx4 v[46:49], v[8:9], off
	global_load_dwordx4 v[50:53], v[10:11], off
	v_pk_add_f32 v[2:3], v[2:3], v[0:1] op_sel_hi:[1,0] neg_lo:[0,1] neg_hi:[0,1]
	v_pk_add_f32 v[4:5], v[4:5], v[0:1] op_sel_hi:[1,0] neg_lo:[0,1] neg_hi:[0,1]
	v_pk_mul_f32 v[66:67], v[2:3], v[2:3]
	v_pk_add_f32 v[30:31], v[30:31], v[0:1] op_sel_hi:[1,0] neg_lo:[0,1] neg_hi:[0,1]
	v_pk_add_f32 v[32:33], v[32:33], v[0:1] op_sel_hi:[1,0] neg_lo:[0,1] neg_hi:[0,1]
	v_pk_mul_f32 v[64:65], v[4:5], v[4:5]
	v_add_f32_e32 v0, v66, v67
	v_add_f32_e32 v0, v64, v0
	v_pk_mul_f32 v[38:39], v[34:35], v[34:35]
	v_add_f32_e32 v0, v65, v0
	v_add_f32_e32 v0, v38, v0
	v_pk_mul_f32 v[54:55], v[36:37], v[36:37]
	v_add_f32_e32 v0, v39, v0
	v_add_f32_e32 v0, v54, v0
	v_pk_mul_f32 v[56:57], v[30:31], v[30:31]
	v_add_f32_e32 v0, v55, v0
	v_add_f32_e32 v0, v56, v0
	v_pk_mul_f32 v[58:59], v[32:33], v[32:33]
	v_add_f32_e32 v0, v57, v0
	v_add_f32_e32 v0, v58, v0
	v_pk_mul_f32 v[60:61], v[26:27], v[26:27]
	v_add_f32_e32 v0, v59, v0
	v_add_f32_e32 v0, v60, v0
	v_pk_mul_f32 v[62:63], v[28:29], v[28:29]
	v_add_f32_e32 v0, v61, v0
	v_add_f32_e32 v0, v62, v0
	v_add_f32_e32 v0, v63, v0
	s_nop 1
	v_add_f32_dpp v0, v0, v0 quad_perm:[1,0,3,2] row_mask:0xf bank_mask:0xf
	s_nop 1
	v_add_f32_dpp v0, v0, v0 quad_perm:[2,3,0,1] row_mask:0xf bank_mask:0xf
	s_nop 1
	v_add_f32_dpp v0, v0, v0 row_half_mirror row_mask:0xf bank_mask:0xf
	s_nop 1
	v_add_f32_dpp v0, v0, v0 row_mirror row_mask:0xf bank_mask:0xf
	s_nop 1
	v_readlane_b32 s8, v0, 0
	v_readlane_b32 s9, v0, 16
	v_readlane_b32 s10, v0, 32
	v_readlane_b32 s11, v0, 48
	s_nop 1
	v_mov_b32_e32 v0, s8
	v_add_f32_e32 v0, s9, v0
	v_add_f32_e32 v0, s10, v0
	v_add_f32_e32 v0, s11, v0
	v_fmamk_f32 v0, v0, 0x3a800000, v162
	v_cmp_gt_f32_e32 vcc, s0, v0
	v_mul_f32_e32 v7, 0x4b800000, v0
	s_nop 0
	v_cndmask_b32_e32 v0, v0, v7, vcc
	v_rsq_f32_e32 v0, v0
	s_nop 0
	v_mul_f32_e32 v7, 0x45800000, v0
	v_cndmask_b32_e32 v38, v0, v7, vcc
	v_pk_mul_f32 v[2:3], v[2:3], v[38:39] op_sel_hi:[1,0]
	v_pk_mul_f32 v[4:5], v[4:5], v[38:39] op_sel_hi:[1,0]
	v_cndmask_b32_e64 v0, 0, 1, s[2:3]
	v_cmp_ne_u32_e64 s[0:1], 1, v0
	s_andn2_b64 vcc, exec, s[2:3]
	s_waitcnt vmcnt(0)
	v_pk_fma_f32 v[2:3], v[46:47], v[2:3], v[50:51]
	v_pk_fma_f32 v[4:5], v[48:49], v[4:5], v[52:53]
	global_store_dwordx4 v[24:25], v[2:5], off
	s_cbranch_vccnz .LBB0_1060
	s_nop 0
	v_cvt_pk_bf16_f32 v2, v2, v3
	v_cvt_pk_bf16_f32 v3, v4, v5
	v_lshl_add_u64 v[4:5], v[22:23], 1, v[12:13]
	global_store_dwordx2 v[4:5], v[2:3], off
